# retention intra-chunk loop: V-fragment reads use one base plus ds offsets (8 address adds removed); decay masks applied only on the diagonal key-tile pair (off-diagonal pairs are fully causal)
# baseline (speedup 1.0000x reference)
.LBB0_121:
	s_nop 1
	v_pk_mul_f32 v[106:107], v[164:165], v[106:107]
	v_pk_mul_f32 v[104:105], v[162:163], v[104:105]
	v_pk_mul_f32 v[110:111], v[164:165], v[110:111]
	v_pk_mul_f32 v[108:109], v[162:163], v[108:109]
	v_pk_mul_f32 v[114:115], v[164:165], v[114:115]
	v_pk_mul_f32 v[112:113], v[162:163], v[112:113]
	v_pk_mul_f32 v[118:119], v[164:165], v[118:119]
	s_andn2_b64 vcc, exec, s[4:5]
	v_pk_mul_f32 v[116:117], v[162:163], v[116:117]
	s_cbranch_vccnz .LBB0_128
	s_mov_b32 s11, 16
	s_mov_b32 s53, 0
	v_mov_b32_e32 v157, v214
	v_mov_b32_e32 v161, v213
	v_mov_b32_e32 v248, v212
	v_add_u32_e32 v249, 0x11000, v211
	s_mov_b32 s54, s39
	s_branch .LBB0_124
.LBB0_123:
	s_nop 7
	ds_read_b64_tr_b16 v[124:125], v249
	ds_read_b64_tr_b16 v[126:127], v249 offset:2560
	ds_read_b64_tr_b16 v[128:129], v249 offset:32
	ds_read_b64_tr_b16 v[130:131], v249 offset:2592
	ds_read_b64_tr_b16 v[132:133], v249 offset:64
	ds_read_b64_tr_b16 v[134:135], v249 offset:2624
	ds_read_b64_tr_b16 v[136:137], v249 offset:96
	ds_read_b64_tr_b16 v[138:139], v249 offset:2656
	v_add_u32_e32 v172, v187, v248
	v_cvt_f32_i32_e32 v173, v172
	s_add_i32 s54, s54, -1
	s_add_i32 s11, s11, 32
	v_fma_f32 v173, v155, v173, -4.0
	s_add_i32 s53, s53, 2
	v_add_u32_e32 v249, 0x1400, v249
	v_subrev_u32_e32 v248, 32, v248
	v_add_u32_e32 v161, 16, v161
	v_add_u32_e32 v157, 0x4400, v157
	s_cmp_eq_u32 s54, 0
	s_cbranch_scc1 .Ldec_masked
	v_exp_f32_e32 v174, v173
	v_fmamk_f32 v175, v155, 0xbf800000, v173
	v_exp_f32_e32 v175, v175
	s_nop 0
	v_mul_f32_e32 v140, v174, v140
	v_mul_f32_e32 v141, v175, v141
	v_fmamk_f32 v174, v155, 0xc0000000, v173
	v_exp_f32_e32 v174, v174
	v_fmamk_f32 v175, v155, 0xc0400000, v173
	v_exp_f32_e32 v175, v175
	s_nop 0
	v_mul_f32_e32 v142, v174, v142
	v_mul_f32_e32 v143, v175, v143
	v_fmamk_f32 v174, v155, 0xc1800000, v173
	v_exp_f32_e32 v174, v174
	v_fmamk_f32 v175, v155, 0xc1880000, v173
	v_exp_f32_e32 v175, v175
	s_nop 0
	v_mul_f32_e32 v120, v174, v120
	v_mul_f32_e32 v121, v175, v121
	v_fmamk_f32 v174, v155, 0xc1900000, v173
	v_exp_f32_e32 v174, v174
	v_fmamk_f32 v175, v155, 0xc1980000, v173
	v_exp_f32_e32 v175, v175
	s_nop 0
	v_mul_f32_e32 v122, v174, v122
	v_mul_f32_e32 v123, v175, v123
	s_branch .Ldec_pack
.Ldec_masked:
	v_exp_f32_e32 v174, v173
	v_fmamk_f32 v175, v155, 0xbf800000, v173
	v_exp_f32_e32 v175, v175
	v_cmp_le_i32_e32 vcc, 0, v172
	v_cmp_le_i32_e64 s[100:101], 1, v172
	v_mul_f32_e32 v140, v174, v140
	v_mul_f32_e32 v141, v175, v141
	v_cndmask_b32_e32 v140, 0, v140, vcc
	v_cndmask_b32_e64 v141, 0, v141, s[100:101]
	v_fmamk_f32 v174, v155, 0xc0000000, v173
	v_exp_f32_e32 v174, v174
	v_fmamk_f32 v175, v155, 0xc0400000, v173
	v_exp_f32_e32 v175, v175
	v_cmp_le_i32_e32 vcc, 2, v172
	v_cmp_le_i32_e64 s[100:101], 3, v172
	v_mul_f32_e32 v142, v174, v142
	v_mul_f32_e32 v143, v175, v143
	v_cndmask_b32_e32 v142, 0, v142, vcc
	v_cndmask_b32_e64 v143, 0, v143, s[100:101]
	v_fmamk_f32 v174, v155, 0xc1800000, v173
	v_exp_f32_e32 v174, v174
	v_fmamk_f32 v175, v155, 0xc1880000, v173
	v_exp_f32_e32 v175, v175
	v_cmp_le_i32_e32 vcc, 16, v172
	v_cmp_le_i32_e64 s[100:101], 17, v172
	v_mul_f32_e32 v120, v174, v120
	v_mul_f32_e32 v121, v175, v121
	v_cndmask_b32_e32 v120, 0, v120, vcc
	v_cndmask_b32_e64 v121, 0, v121, s[100:101]
	v_fmamk_f32 v174, v155, 0xc1900000, v173
	v_exp_f32_e32 v174, v174
	v_fmamk_f32 v175, v155, 0xc1980000, v173
	v_exp_f32_e32 v175, v175
	v_cmp_le_i32_e32 vcc, 18, v172
	v_cmp_le_i32_e64 s[100:101], 19, v172
	v_mul_f32_e32 v122, v174, v122
	v_mul_f32_e32 v123, v175, v123
	v_cndmask_b32_e32 v122, 0, v122, vcc
	v_cndmask_b32_e64 v123, 0, v123, s[100:101]
.Ldec_pack:
	v_cvt_pk_bf16_f32 v174, v120, v121
	v_cvt_pk_bf16_f32 v123, v122, v123
	v_cvt_pk_bf16_f32 v120, v140, v141
	v_cvt_pk_bf16_f32 v121, v142, v143
	v_mov_b32_e32 v122, v174
	s_waitcnt lgkmcnt(6)
	s_nop 0
	v_mfma_f32_16x16x32_bf16 v[104:107], v[124:127], v[120:123], v[104:107]
	s_waitcnt lgkmcnt(4)
	v_mfma_f32_16x16x32_bf16 v[108:111], v[128:131], v[120:123], v[108:111]
	s_waitcnt lgkmcnt(2)
	v_mfma_f32_16x16x32_bf16 v[112:115], v[132:135], v[120:123], v[112:115]
	s_waitcnt lgkmcnt(0)
	v_mfma_f32_16x16x32_bf16 v[116:119], v[136:139], v[120:123], v[116:119]
	s_cbranch_scc1 .LBB0_128
